# attention phase rebalanced: every workgroup takes half a sample unit (2 of 4 query positions) and 2 SGU units
# speedup vs baseline: 1.0612x; 1.0139x over previous
; #define LAS __attribute__((address_space(3)))
; __device__ __forceinline__ int lane_id_v() { int l; asm volatile("v_mbcnt_lo_u32_b32 %0, -1, 0\n\tv_mbcnt_hi_u32_b32 %0, -1, %0" : "=v"(l)); return l; }
; __global__ void __launch_bounds__(NWAVES * 64, 2) mega(Args args) {
;     ...
;     unsigned char* ws = args.ws; float* out = args.out;
;     float* ROPE = (float*)(ws + WS_ROPE);
;     bf16_t* WIN = (bf16_t*)(ws + WS_WIN); bf16_t* WMIX = (bf16_t*)(ws + WS_WMIX); bf16_t* WXQ = (bf16_t*)(ws + WS_WXQ); bf16_t* WXKV = (bf16_t*)(ws + WS_WXKV);
;     bf16_t* WXO = (bf16_t*)(ws + WS_WXO); bf16_t* WUP = (bf16_t*)(ws + WS_WUP); bf16_t* WDN = (bf16_t*)(ws + WS_WDN); bf16_t* WSP = (bf16_t*)(ws + WS_WSP);
;     bf16_t* MEMB = (bf16_t*)(ws + WS_MEMB); bf16_t* MKV = (bf16_t*)(ws + WS_MKV);
;     bf16_t* XB = (bf16_t*)(ws + WS_XB);
;     bf16_t* Qb = (bf16_t*)(ws + WS_Q); bf16_t* Kb = (bf16_t*)(ws + WS_K); bf16_t* Vb = (bf16_t*)(ws + WS_V); bf16_t* Ub = (bf16_t*)(ws + WS_U); bf16_t* Gb = (bf16_t*)(ws + WS_G);
;     bf16_t* CAT = (bf16_t*)(ws + WS_CAT); float* LSE = (float*)(ws + WS_LSE);
;     bf16_t* XQ = (bf16_t*)(ws + WS_XQ); bf16_t* XO = (bf16_t*)(ws + WS_XO); bf16_t* H = (bf16_t*)(ws + WS_H);
;     const int lo = args.ph_lo, hi = args.ph_hi;
;     int ph = 0;
;     cg::grid_group grid = cg::this_grid();
;     volatile LAS unsigned* misc = (volatile LAS unsigned*)(lds + LDS_BYTES - 64);
;     if (wave == 0) { const int l0 = lane_id_v(); if (l0 < 2) misc[l0] = 0u; }
;     __syncthreads();
;     XcdBarrier xbar; xbar.bar = g_bar; xbar.x = 0; xbar.st = misc;
;     if (hi - lo > 1) xbar = xcd_barrier_post(g_bar, misc, wave);
;     if (lo < 0) grid.sync();
;     ...
;     float* CV = (float*)(ws + WS_CV); float* CVP = (float*)(ws + WS_CVP); float* STM = (float*)(ws + WS_STM); float* STS = (float*)(ws + WS_STS); float* GST = (float*)(ws + WS_GST); bf16_t* ZB = (bf16_t*)(ws + WS_ZB);
.LBB0_201:
	s_add_u32 s0, s94, 0x5364100
	v_writelane_b32 v251, s88, 63
	s_addc_u32 s1, s95, 0
	v_readlane_b32 s24, v251, 0
	v_writelane_b32 v252, s89, 0
	v_writelane_b32 v252, s0, 1
	v_readlane_b32 s26, v251, 2
	s_mov_b32 s78, s90
	v_writelane_b32 v252, s1, 2
	s_add_u32 s0, s94, 0x5694100
	v_writelane_b32 v252, s0, 3
	s_addc_u32 s0, s95, 0
	v_writelane_b32 v252, s0, 4
	s_add_u32 s0, s94, 0x5a94100
	v_writelane_b32 v252, s0, 5
	s_addc_u32 s0, s95, 0
	s_add_u32 s6, s94, 0x5ab4100
	s_addc_u32 s7, s95, 0
	s_add_u32 s70, s94, 0x5b34100
	s_addc_u32 s71, s95, 0
	v_writelane_b32 v252, s0, 6
	s_add_u32 s0, s94, 0x3f24100
	s_addc_u32 s1, s95, 0
	v_writelane_b32 v252, s0, 7
	v_readlane_b32 s27, v251, 3
	v_readlane_b32 s25, v251, 1
	v_writelane_b32 v252, s1, 8
	s_add_u32 s0, s94, 0x4364100
	v_writelane_b32 v252, s0, 9
	s_addc_u32 s0, s95, 0
	s_add_u32 s88, s94, 0x9c34100
	s_addc_u32 s89, s95, 0
	v_writelane_b32 v252, s0, 10
	s_add_u32 s0, s94, 0xb494100
	s_addc_u32 s1, s95, 0
	v_writelane_b32 v252, s0, 11
	v_mov_b32_e32 v2, 0
	v_mov_b32_e32 v220, 1
	v_writelane_b32 v252, s1, 12
	s_add_u32 s0, s94, 0xccf4100
	s_addc_u32 s1, s95, 0
	v_writelane_b32 v252, s0, 13
	v_mov_b32_e32 v221, 0x3727c5ac
	v_mov_b32_e32 v222, 0x800
	v_writelane_b32 v252, s1, 14
	s_add_u32 s0, s94, 0xe554100
	s_addc_u32 s1, s95, 0
	v_writelane_b32 v252, s0, 15
	v_mov_b64_e32 v[170:171], 0x2bf
	v_mov_b32_e32 v223, 0x2d60000
	v_writelane_b32 v252, s1, 16
	s_add_u32 s0, s94, 0xed74100
	s_addc_u32 s1, s95, 0
	s_add_u32 s74, s94, 0xf594100
	v_writelane_b32 v252, s0, 17
	s_addc_u32 s75, s95, 0
	v_mov_b32_e32 v224, 0x2d40000
	v_writelane_b32 v252, s1, 18
	s_add_u32 s0, s94, 0x11718100
	s_addc_u32 s1, s95, 0
	s_add_u32 s28, s94, 0x13798100
	s_addc_u32 s29, s95, 0
	v_writelane_b32 v252, s0, 19
	s_add_u32 s30, s94, 0x15818100
	s_addc_u32 s31, s95, 0
	v_writelane_b32 v252, s1, 20
	s_lshr_b32 s0, s2, 8
	s_lshl_b32 s1, s0, 6
	s_bfe_u32 s33, s2, 0x20006
	v_writelane_b32 v252, s1, 21
	s_lshl_b32 s1, s0, 13
	v_writelane_b32 v252, s1, 22
	s_lshl_b32 s1, s33, 5
	s_lshl_b32 s87, s86, 10
	v_writelane_b32 v252, s1, 23
	s_lshl_b32 s1, s33, 12
	s_cmpk_lt_i32 s91, 0x2c0
	v_writelane_b32 v252, s1, 24
	s_cselect_b64 s[4:5], -1, 0
	v_writelane_b32 v252, s4, 25
	s_ashr_i32 s1, s91, 31
	s_add_i32 s85, s87, 0
	v_writelane_b32 v252, s5, 26
	v_writelane_b32 v252, s1, 27
	s_lshr_b32 s1, s1, 29
	s_add_i32 s1, s91, s1
	s_ashr_i32 s5, s1, 3
	s_and_b32 s1, s1, -8
	s_sub_i32 s4, s91, s1
	s_cmp_eq_u32 s0, 1
	s_cselect_b64 s[34:35], -1, 0
	s_cmpk_lt_u32 s2, 0x100
	s_waitcnt lgkmcnt(0)
	s_cselect_b64 s[8:9], -1, 0
	v_writelane_b32 v252, s8, 28
	s_lshl_b32 s1, s33, 1
	v_mov_b32_e32 v225, 0x2d20000
	v_writelane_b32 v252, s9, 29
	v_writelane_b32 v252, s1, 30
	s_ashr_i32 s1, s26, 31
	v_writelane_b32 v252, s1, 31
	s_lshl_b32 s1, s33, 3
	s_add_u32 s8, s6, s1
	v_writelane_b32 v252, s6, 32
	s_addc_u32 s9, s7, 0
	s_not_b32 s1, s91
	v_writelane_b32 v252, s7, 33
	v_writelane_b32 v252, s8, 34
	s_add_i32 s1, s26, s1
	s_cmpk_lt_i32 s1, 0xb0
	v_writelane_b32 v252, s9, 35
	v_writelane_b32 v252, s1, 36
	s_cselect_b64 s[6:7], -1, 0
	v_writelane_b32 v252, s6, 37
	s_lshl_b32 s22, s86, 4
	s_and_b32 s36, s22, 0x70
	v_writelane_b32 v252, s7, 38
	s_lshl_b32 s1, s2, 1
	s_sub_i32 s6, s26, 64
	s_cmp_ge_i32 s91, s6
	s_cselect_b64 s[8:9], -1, 0
	v_writelane_b32 v252, s8, 39
	s_sub_i32 s7, s91, s6
	s_lshl_b32 s6, s86, 5
	v_writelane_b32 v252, s9, 40
	v_writelane_b32 v252, s6, 41
	s_and_b32 s6, s6, 0x60
	v_writelane_b32 v252, s6, 42
	s_lshr_b32 s6, s6, 3
	s_cmp_lt_i32 s7, 64
	v_writelane_b32 v252, s6, 43
	s_cselect_b64 s[8:9], -1, 0
	v_writelane_b32 v252, s8, 44
	s_ashr_i32 s6, s7, 31
	v_mov_b32_e32 v226, 0xfffffa00
	v_writelane_b32 v252, s9, 45
	v_writelane_b32 v252, s6, 46
	s_lshr_b32 s6, s6, 29
	s_add_i32 s6, s7, s6
	s_ashr_i32 s10, s6, 3
	s_and_b32 s6, s6, -8
	s_sub_i32 s11, s7, s6
	s_lshl_b32 s20, s11, 3
	v_writelane_b32 v252, s7, 47
	s_add_u32 s6, s92, 0x9480000
	v_writelane_b32 v252, s6, 48
	s_addc_u32 s6, s93, 0
	s_cmp_eq_u32 s3, 15
	v_writelane_b32 v252, s6, 49
	s_cselect_b64 s[6:7], -1, 0
	v_writelane_b32 v252, s6, 50
	s_cmp_eq_u32 s3, 14
	v_mov_b32_e32 v227, 0xfffff880
	v_writelane_b32 v252, s7, 51
	s_cselect_b64 s[6:7], -1, 0
	v_writelane_b32 v252, s6, 52
	s_cmp_eq_u32 s3, 13
	v_mov_b32_e32 v228, 0x1520000
	v_writelane_b32 v252, s7, 53
	s_cselect_b64 s[6:7], -1, 0
	v_writelane_b32 v252, s6, 54
	s_cmp_eq_u32 s3, 12
	v_mov_b32_e32 v229, 0x1120000
	v_writelane_b32 v252, s7, 55
	s_cselect_b64 s[6:7], -1, 0
	v_writelane_b32 v252, s6, 56
	s_cmp_eq_u32 s3, 11
	v_mov_b32_e32 v230, 0x1020000
	v_writelane_b32 v252, s7, 57
	s_cselect_b64 s[6:7], -1, 0
	v_writelane_b32 v252, s6, 58
	s_cmp_eq_u32 s3, 10
	v_mov_b32_e32 v231, 0x600
	v_writelane_b32 v252, s7, 59
	s_cselect_b64 s[6:7], -1, 0
	v_writelane_b32 v252, s6, 60
	s_cmp_eq_u32 s3, 9
	v_mov_b32_e32 v232, 0xf149f2ca
	v_writelane_b32 v252, s7, 61
	s_cselect_b64 s[6:7], -1, 0
	v_writelane_b32 v252, s6, 62
	s_cmp_eq_u32 s3, 8
	v_mov_b32_e32 v233, 0x41b17218
	v_writelane_b32 v252, s7, 63
	s_cselect_b64 s[6:7], -1, 0
	v_writelane_b32 v253, s6, 0
	s_cmp_eq_u32 s3, 7
	v_mov_b64_e32 v[172:173], 0x100
	v_writelane_b32 v253, s7, 1
	s_cselect_b64 s[6:7], -1, 0
	v_writelane_b32 v253, s6, 2
	s_cmp_eq_u32 s3, 6
	v_mov_b64_e32 v[174:175], 0xff
	v_writelane_b32 v253, s7, 3
	s_cselect_b64 s[6:7], -1, 0
	v_writelane_b32 v253, s6, 4
	s_cmp_eq_u32 s3, 5
	v_mov_b64_e32 v[176:177], 0x400
	v_writelane_b32 v253, s7, 5
	s_cselect_b64 s[6:7], -1, 0
	v_writelane_b32 v253, s6, 6
	s_cmp_eq_u32 s3, 4
	v_mov_b64_e32 v[178:179], 0x3ff
	v_writelane_b32 v253, s7, 7
	s_cselect_b64 s[6:7], -1, 0
	v_writelane_b32 v253, s6, 8
;     __host__ __device__ bool next(int i, Unit& u) const {
;         const long L = (long)i * G + c; if (L >= nwg) return false;
;         int wgid = (int)L; { const int q = nwg / NXCD, r = nwg % NXCD, xcd = wgid % NXCD, off = wgid / NXCD; wgid = (xcd < r ? xcd * (q + 1) : r * (q + 1) + (xcd - r) * q) + off; }
;         const int nig = WGM * nN, gid = wgid / nig, fm = gid * WGM, gsz = (nM - fm) < WGM ? (nM - fm) : WGM;
;         u.pm = fm + ((wgid % nig) % gsz); u.pn = (wgid % nig) / gsz; return true;
; __global__ void __launch_bounds__(NWAVES * 64, 2) mega(Args args) {
;     ...
;             const int nsgu = G == 256 ? (bx < 128 ? 1 : 3) : (128 * 4 - bx + G - 1) / G;
;             for (int ui = 0; ui < nsgu; ++ui) {
;                 const int unit = G == 256 ? (bx < 128 ? bx : 128 + 3 * (bx - 128) + ui) : bx + ui * G;
;                 const int ck = unit >> 2, g = unit & 3; const size_t R0 = (size_t)ck * 128;
	s_cmp_eq_u32 s3, 3
	s_mov_b32 s73, s26
	v_writelane_b32 v253, s7, 9
	s_cselect_b64 s[6:7], -1, 0
	v_writelane_b32 v253, s6, 10
	s_cmp_eq_u32 s3, 2
	s_mov_b32 s76, 0x30000
	v_writelane_b32 v253, s7, 11
	s_cselect_b64 s[6:7], -1, 0
	v_writelane_b32 v253, s6, 12
	s_cmp_eq_u32 s3, 1
	s_mov_b32 s82, 0x3a800000
	v_writelane_b32 v253, s7, 13
	s_cselect_b64 s[6:7], -1, 0
	v_writelane_b32 v253, s6, 14
	s_cmp_eq_u32 s3, 0
	s_mov_b32 s72, 0x3fb504f3
	v_writelane_b32 v253, s7, 15
	s_cselect_b64 s[6:7], -1, 0
	v_writelane_b32 v253, s6, 16
	s_lshl_b32 s3, s3, 8
	s_mov_b32 s84, 0x3db8aa3b
	v_writelane_b32 v253, s7, 17
	s_getpc_b64 s[6:7]
	s_add_u32 s6, s6, g_bar@rel32@lo+5124
	s_addc_u32 s7, s7, g_bar@rel32@hi+5132
	s_add_u32 s6, s6, s3
	s_addc_u32 s7, s7, 0
	v_writelane_b32 v253, s6, 18
	s_nop 1
	v_writelane_b32 v253, s7, 19
	s_getpc_b64 s[6:7]
	s_add_u32 s6, s6, g_bar@rel32@lo+9220
	s_addc_u32 s7, s7, g_bar@rel32@hi+9228
	s_add_u32 s6, s6, s3
	s_addc_u32 s7, s7, 0
	v_writelane_b32 v253, s6, 20
	s_mul_i32 s3, s86, 0x1400
	s_add_i32 s3, s3, 0
	v_writelane_b32 v253, s7, 21
	v_writelane_b32 v253, s3, 22
	s_lshl_b32 s3, s91, 9
	s_and_b32 s83, s2, 0xffffffc0
	v_writelane_b32 v253, s3, 23
	s_lshl_b32 s3, s26, 9
	s_cmpk_lt_u32 s2, 0x300
	v_writelane_b32 v253, s3, 24
	s_cselect_b64 s[6:7], -1, 0
	v_writelane_b32 v253, s6, 25
	s_cmpk_lt_i32 s91, 0x100
	s_nop 0
	v_writelane_b32 v253, s7, 26
	s_cselect_b64 s[6:7], -1, 0
	v_writelane_b32 v253, s6, 27
	s_cmpk_eq_i32 s26, 0x100
	s_nop 0
	v_writelane_b32 v253, s7, 28
	s_cselect_b64 s[6:7], -1, 0
	v_writelane_b32 v253, s6, 29
	s_cmpk_lg_i32 s26, 0x100
	s_cselect_b64 s[38:39], -1, 0
	v_writelane_b32 v253, s7, 30
	s_sub_i32 s7, s26, s91
	s_add_i32 s6, s7, 0x1ff
	s_cmpk_lt_i32 s91, 0x80
	s_cselect_b64 s[8:9], -1, 0
	v_writelane_b32 v253, s8, 31
	s_nop 1
	v_writelane_b32 v253, s9, 32
	s_and_b64 s[8:9], s[8:9], exec
	s_mov_b32 s3, 2
	v_writelane_b32 v253, s3, 33
	s_lshl_b32 s3, s91, 1
	s_nop 0
	v_writelane_b32 v253, s3, 34
	s_and_b32 s8, s1, 0x7fffff00
	s_lshr_b32 s1, s2, 7
	s_lshl_b32 s21, s4, 5
	v_writelane_b32 v253, s22, 35
	s_and_b32 s3, s22, 16
	s_lshl_b32 s22, s8, 1
	v_writelane_b32 v253, s8, 36
	s_add_u32 s8, s74, s22
	s_addc_u32 s9, s75, 0
	v_writelane_b32 v253, s8, 37
	s_cmpk_lt_u32 s2, 0x80
	s_nop 0
	v_writelane_b32 v253, s9, 38
	s_cselect_b64 s[8:9], -1, 0
	v_writelane_b32 v253, s8, 39
	s_nop 1
	v_writelane_b32 v253, s9, 40
	s_add_u32 s8, s70, s22
	s_addc_u32 s9, s71, 0
	v_writelane_b32 v253, s8, 41
	s_cmpk_lt_i32 s91, 0x280
	s_nop 0
	v_writelane_b32 v253, s9, 42
	s_cselect_b64 s[8:9], -1, 0
	s_and_b32 s23, s91, 7
	s_ashr_i32 s37, s91, 3
	v_writelane_b32 v253, s8, 43
	s_cmp_lt_i32 s37, 16
	s_nop 0
	v_writelane_b32 v253, s9, 44
	s_cselect_b64 s[8:9], -1, 0
	v_writelane_b32 v253, s8, 45
	s_nop 1
	v_writelane_b32 v253, s9, 46
	s_and_b64 s[8:9], s[8:9], exec
	s_cselect_b32 s8, 2, 3
	v_writelane_b32 v253, s8, 47
	s_mul_i32 s8, s37, 3
	s_sub_i32 s8, s8, 32
	v_writelane_b32 v253, s8, 48
	v_writelane_b32 v253, s23, 49
	s_lshl_b32 s8, s23, 4
	v_writelane_b32 v253, s37, 50
	s_add_i32 s8, s8, s37
	v_writelane_b32 v253, s8, 51
	s_add_u32 s8, s28, s22
	s_addc_u32 s9, s29, 0
	v_writelane_b32 v253, s8, 52
	s_cmpk_lt_i32 s91, 0x400
	s_nop 0
	v_writelane_b32 v253, s9, 53
	s_cselect_b64 s[8:9], -1, 0
	v_writelane_b32 v253, s8, 54
	s_nop 1
	v_writelane_b32 v253, s9, 55
	s_lshl_b32 s8, s4, 7
	s_cmp_lt_i32 s4, 0
	s_mul_i32 s9, s4, 33
	s_cselect_b32 s21, s9, s21
	s_movk_i32 s9, 0x59
	s_cselect_b32 s9, s9, 0x58
	s_mul_i32 s9, s4, s9
	s_mulk_i32 s4, 0x81
	s_cselect_b32 s22, s4, s8
	s_add_i32 s9, s9, s5
	s_mul_hi_i32 s4, s9, 0x2e8ba2e9
	s_lshr_b32 s8, s4, 31
	s_ashr_i32 s4, s4, 4
	s_add_i32 s4, s4, s8
	s_mul_i32 s8, s4, 0x58
	s_sub_i32 s8, s9, s8
	s_bfe_i32 s9, s8, 0x80000
	s_bfe_u32 s9, s9, 0x3000c
	s_add_i32 s9, s8, s9
	s_and_b32 s23, s9, 0xf8
	s_sub_i32 s8, s8, s23
	s_bfe_i32 s9, s9, 0x80000
	s_lshl_b32 s4, s4, 3
	s_sext_i32_i16 s9, s9
	s_sext_i32_i8 s8, s8
	s_add_i32 s40, s4, s8
	s_ashr_i32 s4, s9, 3
	v_writelane_b32 v253, s4, 56
	s_lshr_b32 s4, s9, 3
	s_cmp_lt_i32 s11, 0
	s_mul_i32 s11, s11, 9
	s_cselect_b32 s8, s11, s20
	s_add_i32 s8, s8, s10
	s_ashr_i32 s9, s8, 31
	s_lshr_b32 s9, s9, 26
	s_add_i32 s9, s8, s9
	s_and_b32 s10, s9, 0xffc0
	s_sub_i32 s8, s8, s10
	s_bfe_i32 s10, s8, 0x80000
	s_bfe_u32 s10, s10, 0x3000c
	s_add_i32 s10, s8, s10
	s_and_b32 s11, s10, 0xf8
	s_sub_i32 s8, s8, s11
	s_ashr_i32 s9, s9, 6
	s_bfe_i32 s10, s10, 0x80000
	s_lshl_b32 s9, s9, 3
	s_sext_i32_i16 s10, s10
	s_sext_i32_i8 s8, s8
	s_add_i32 s42, s9, s8
	s_ashr_i32 s8, s10, 3
	v_writelane_b32 v253, s8, 57
	s_lshr_b32 s8, s10, 3
	s_bfe_i64 s[8:9], s[8:9], 0x100000
	s_lshl_b64 s[8:9], s[8:9], 19
	v_writelane_b32 v253, s8, 58
	s_ashr_i32 s43, s42, 31
	v_readlane_b32 s10, v251, 56
	v_writelane_b32 v253, s9, 59
	s_mov_b32 s8, s42
	v_writelane_b32 v253, s8, 60
	s_nop 1
	v_writelane_b32 v253, s9, 61
	s_lshl_b64 s[8:9], s[42:43], 19
	s_add_u32 s10, s10, s8
	v_readlane_b32 s8, v251, 57
	s_addc_u32 s11, s8, s9
	s_add_u32 s8, s10, 0x40000
	v_writelane_b32 v253, s10, 62
	s_addc_u32 s9, s11, 0
	v_writelane_b32 v254, s8, 0
	v_writelane_b32 v253, s11, 63
	s_nop 0
	v_writelane_b32 v254, s9, 1
	s_add_i32 s8, s21, s5
	s_ashr_i32 s9, s8, 31
	s_lshr_b32 s9, s9, 27
	s_add_i32 s9, s8, s9
	s_and_b32 s10, s9, 0xffe0
	s_sub_i32 s8, s8, s10
	s_bfe_i32 s10, s8, 0x80000
	s_bfe_u32 s10, s10, 0x3000c
	s_add_i32 s10, s8, s10
	s_and_b32 s11, s10, 0xf8
	s_sub_i32 s8, s8, s11
	s_lshl_b32 s11, s33, 2
	s_add_i32 s11, s11, 0
	s_ashr_i32 s9, s9, 5
	s_bfe_i32 s10, s10, 0x80000
	s_add_i32 s11, s11, 0x22000
	s_lshl_b32 s9, s9, 3
	s_sext_i32_i16 s10, s10
	s_sext_i32_i8 s8, s8
	v_writelane_b32 v254, s11, 2
;     __host__ __device__ bool next(int i, Unit& u) const {
;         const long L = (long)i * G + c; if (L >= nwg) return false;
;         int wgid = (int)L; { const int q = nwg / NXCD, r = nwg % NXCD, xcd = wgid % NXCD, off = wgid / NXCD; wgid = (xcd < r ? xcd * (q + 1) : r * (q + 1) + (xcd - r) * q) + off; }
;         const int nig = WGM * nN, gid = wgid / nig, fm = gid * WGM, gsz = (nM - fm) < WGM ? (nM - fm) : WGM;
;         u.pm = fm + ((wgid % nig) % gsz); u.pn = (wgid % nig) / gsz; return true;
;     }
; __global__ void __launch_bounds__(NWAVES * 64, 2) mega(Args args) {
;     ...
;             const int nsgu = G == 256 ? (bx < 128 ? 1 : 3) : (128 * 4 - bx + G - 1) / G;
;             for (int ui = 0; ui < nsgu; ++ui) {
;                 const int unit = G == 256 ? (bx < 128 ? bx : 128 + 3 * (bx - 128) + ui) : bx + ui * G;
	s_add_i32 s42, s9, s8
	s_ashr_i32 s8, s10, 3
	v_writelane_b32 v254, s8, 3
	s_lshr_b32 s8, s10, 3
	s_bfe_i64 s[8:9], s[8:9], 0x100000
	s_or_b32 s10, s3, 0x4000
	s_ashr_i32 s43, s42, 31
	v_writelane_b32 v254, s10, 4
	s_lshl_b64 s[20:21], s[8:9], 19
	s_lshl_b64 s[10:11], s[42:43], 19
	v_writelane_b32 v254, s20, 5
	s_nop 1
	v_writelane_b32 v254, s21, 6
	s_add_u32 s20, s70, s10
	s_addc_u32 s21, s71, s11
	s_add_u32 s44, s20, 0x40000
	v_writelane_b32 v254, s20, 7
	s_addc_u32 s45, s21, 0
	s_add_i32 s5, s22, s5
	v_writelane_b32 v254, s21, 8
	s_ashr_i32 s20, s5, 31
	s_lshr_b32 s20, s20, 25
	s_add_i32 s20, s5, s20
	s_and_b32 s21, s20, 0xff80
	s_sub_i32 s5, s5, s21
	s_bfe_i32 s21, s5, 0x80000
	s_bfe_u32 s21, s21, 0x3000c
	s_add_i32 s21, s5, s21
	s_and_b32 s22, s21, 0xf8
	s_sub_i32 s5, s5, s22
	s_ashr_i32 s20, s20, 7
	s_bfe_i32 s21, s21, 0x80000
	s_lshl_b32 s20, s20, 3
	s_sext_i32_i16 s21, s21
	s_sext_i32_i8 s5, s5
	v_writelane_b32 v254, s44, 9
	s_add_i32 s22, s20, s5
	s_lshr_b32 s20, s21, 3
	v_writelane_b32 v254, s45, 10
	s_ashr_i32 s5, s21, 3
	s_bfe_i64 s[20:21], s[20:21], 0x100000
	v_writelane_b32 v254, s5, 11
	s_lshl_b64 s[20:21], s[20:21], 19
	v_writelane_b32 v254, s20, 12
	s_ashr_i32 s23, s22, 31
	s_nop 0
	v_writelane_b32 v254, s21, 13
	s_mov_b32 s20, s22
	v_writelane_b32 v254, s20, 14
	s_nop 1
	v_writelane_b32 v254, s21, 15
	s_lshl_b64 s[20:21], s[22:23], 19
	s_add_u32 s22, s70, s20
	s_addc_u32 s23, s71, s21
	s_mov_b64 s[20:21], s[38:39]
	s_add_u32 s38, s22, 0x40000
	v_writelane_b32 v254, s22, 16
	s_addc_u32 s39, s23, 0
	s_bfe_i64 s[4:5], s[4:5], 0x100000
	v_writelane_b32 v254, s23, 17
	v_writelane_b32 v254, s38, 18
	s_lshl_b64 s[4:5], s[4:5], 19
	s_ashr_i32 s41, s40, 31
	v_writelane_b32 v254, s39, 19
	v_writelane_b32 v254, s4, 20
	s_nop 1
	v_writelane_b32 v254, s5, 21
	v_writelane_b32 v254, s36, 22
	s_or_b32 s4, s36, 0x4000
	v_writelane_b32 v254, s4, 23
	s_mov_b32 s4, s40
	v_writelane_b32 v254, s4, 24
	s_nop 1
	v_writelane_b32 v254, s5, 25
	s_lshl_b64 s[4:5], s[40:41], 19
	v_writelane_b32 v254, s4, 26
	s_nop 1
	v_writelane_b32 v254, s5, 27
	s_add_u32 s4, s74, s10
	s_addc_u32 s5, s75, s11
	s_add_u32 s22, s4, 0x40000
	v_writelane_b32 v254, s4, 28
	s_addc_u32 s23, s5, 0
	s_nop 0
	v_writelane_b32 v254, s5, 29
	v_writelane_b32 v254, s22, 30
	s_add_u32 s4, s28, s10
	s_nop 0
	v_writelane_b32 v254, s23, 31
	v_writelane_b32 v254, s28, 32
	s_addc_u32 s5, s29, s11
	s_add_u32 s10, s4, 0x40000
	v_writelane_b32 v254, s29, 33
	v_writelane_b32 v254, s4, 34
	s_addc_u32 s11, s5, 0
	s_movk_i32 s28, 0x600
	v_writelane_b32 v254, s5, 35
	v_writelane_b32 v254, s10, 36
	s_lshl_b64 s[4:5], s[8:9], 21
	s_nop 0
	v_writelane_b32 v254, s11, 37
	v_writelane_b32 v254, s4, 38
	s_nop 1
	v_writelane_b32 v254, s5, 39
	s_mov_b32 s4, s42
	v_writelane_b32 v254, s4, 40
	s_nop 1
	v_writelane_b32 v254, s5, 41
	s_lshl_b64 s[4:5], s[42:43], 21
	s_add_u32 s4, s30, s4
	v_writelane_b32 v254, s30, 42
	s_addc_u32 s5, s31, s5
	s_add_u32 s8, s4, 0x100000
	v_writelane_b32 v254, s31, 43
	v_writelane_b32 v254, s4, 44
	s_addc_u32 s9, s5, 0
	s_mov_b32 s31, 0xf149f2ca
	v_writelane_b32 v254, s5, 45
	s_abs_i32 s4, s26
	v_cvt_f32_u32_e32 v0, s4
	v_writelane_b32 v254, s8, 46
	s_sub_i32 s5, 0, s4
	v_rcp_iflag_f32_e32 v0, v0
	v_writelane_b32 v254, s9, 47
	v_writelane_b32 v254, s34, 48
	v_mul_f32_e32 v0, 0x4f7ffffe, v0
	v_cvt_u32_f32_e32 v0, v0
	v_writelane_b32 v254, s35, 49
	v_cndmask_b32_e64 v218, 0, 1, s[34:35]
	s_mov_b64 s[34:35], 0x400
	v_readfirstlane_b32 s8, v0
	s_mul_i32 s5, s5, s8
	s_mul_hi_u32 s5, s8, s5
	s_add_i32 s8, s8, s5
	s_sub_i32 s5, 0xfffffe01, s7
	s_max_i32 s5, s6, s5
	s_mul_hi_u32 s7, s5, s8
	s_mul_i32 s8, s7, s4
	s_sub_i32 s5, s5, s8
	s_xor_b32 s6, s6, s26
	s_ashr_i32 s6, s6, 31
	s_add_i32 s8, s7, 1
	s_sub_i32 s9, s5, s4
	s_cmp_ge_u32 s5, s4
	s_cselect_b32 s7, s8, s7
	s_cselect_b32 s5, s9, s5
	s_add_i32 s8, s7, 1
	s_cmp_ge_u32 s5, s4
	s_cselect_b32 s4, s8, s7
	s_xor_b32 s4, s4, s6
	s_sub_i32 s4, s4, s6
	s_lshl_b32 s2, s2, 2
	v_writelane_b32 v254, s4, 50
	s_and_b32 s2, s2, 0xfffff800
	v_writelane_b32 v254, s2, 51
	s_add_u32 s2, s94, s2
	s_addc_u32 s4, s95, 0
	s_add_u32 s5, s2, 0x24300
	v_writelane_b32 v254, s5, 52
	s_addc_u32 s5, s4, 0
	v_writelane_b32 v254, s5, 53
	s_lshl_b32 s5, s26, 4
	s_lshl_b32 s6, s91, 4
	v_writelane_b32 v254, s5, 54
	s_sub_i32 s5, s5, s6
	v_writelane_b32 v254, s6, 55
	s_add_i32 s5, s5, -16
	v_writelane_b32 v254, s5, 56
	s_lshl_b32 s5, s86, 7
	s_add_i32 s5, s5, 0
	s_add_i32 s5, s5, 0xa000
	v_writelane_b32 v254, s5, 57
	s_lshl_b32 s0, s0, 1
	v_writelane_b32 v254, s0, 58
	s_lshl_b32 s0, s86, 11
	s_add_i32 s0, s0, 0
	s_add_i32 s0, s0, 0xa000
	v_writelane_b32 v254, s0, 59
	s_lshl_b32 s0, s26, 5
	v_writelane_b32 v254, s0, 60
	s_add_u32 s0, s92, 0xb600800
	v_writelane_b32 v254, s0, 61
	s_addc_u32 s0, s93, 0
	v_writelane_b32 v254, s0, 62
	s_lshl_b32 s0, s91, 5
	s_or_b32 s0, s0, s3
	v_writelane_b32 v250, s0, 0
	s_addk_i32 s0, 0x4000
	s_ashr_i32 s79, s90, 31
	v_writelane_b32 v250, s0, 1
	v_writelane_b32 v250, s78, 2
	s_lshl_b64 s[6:7], s[78:79], 12
	s_add_i32 s3, s1, 1
	v_writelane_b32 v250, s79, 3
	v_writelane_b32 v250, s6, 4
	s_add_u32 s0, s2, 0x1f24300
	v_writelane_b32 v254, s3, 63
	v_writelane_b32 v250, s7, 5
	v_writelane_b32 v250, s0, 6
	s_addc_u32 s0, s4, 0
	s_add_u32 s2, s2, 0x5b34300
	v_writelane_b32 v250, s0, 7
	s_addc_u32 s3, s4, 0
	v_writelane_b32 v250, s2, 8
	s_lshl_b32 s0, s1, 11
	s_add_u32 s0, s94, s0
	v_writelane_b32 v250, s3, 9
	v_writelane_b32 v250, s92, 10
	s_addc_u32 s1, s95, 0
	s_add_u32 s2, s0, 0x2f24300
	v_writelane_b32 v250, s93, 11
	v_writelane_b32 v250, s94, 12
	v_writelane_b32 v250, s95, 13
	v_writelane_b32 v250, s2, 14
	s_addc_u32 s2, s1, 0
	s_add_u32 s0, s0, 0x15818300
	v_writelane_b32 v250, s2, 15
	s_addc_u32 s1, s1, 0
	v_writelane_b32 v250, s0, 16
	s_mov_b32 s5, 0
	s_movk_i32 s3, 0x100
	v_writelane_b32 v250, s1, 17
	s_mul_i32 s0, s96, s27
	v_writelane_b32 v250, s96, 18
	s_mul_i32 s0, s0, s26
	v_writelane_b32 v250, s0, 19
	s_mov_b32 s0, 1
	v_writelane_b32 v250, s0, 20
	s_add_i32 s0, 0, 0x23fc0
	v_writelane_b32 v250, s0, 21
	s_add_i32 s0, 0, 0x23fc4
	v_writelane_b32 v250, s0, 22
	s_add_i32 s0, 0, 0xa60
	v_writelane_b32 v250, s0, 23
	s_mov_b64 s[0:1], -1
	v_writelane_b32 v250, s0, 24
	v_mbcnt_lo_u32_b32 v0, -1, 0
	v_mbcnt_hi_u32_b32 v219, -1, v0
	v_writelane_b32 v250, s1, 25
	s_mov_b32 s0, s5
	v_writelane_b32 v250, s0, 26
	s_mov_b32 s79, 0x10000
	s_mov_b32 s78, 0x20000
	v_writelane_b32 v250, s1, 27
	v_readlane_b32 s0, v251, 58
	v_readlane_b32 s1, v251, 59
	s_add_i32 s94, 0, 0x11000
	v_writelane_b32 v250, s0, 28
	s_mov_b64 s[96:97], 0
	s_mov_b64 s[92:93], 0x80
	v_writelane_b32 v250, s1, 29
	v_writelane_b32 v250, s70, 30
	s_mov_b32 s8, s5
	s_nop 0
	v_writelane_b32 v250, s71, 31
	v_writelane_b32 v250, s20, 32
	s_nop 1
	v_writelane_b32 v250, s21, 33
	v_writelane_b32 v250, s91, 34
	s_branch .LBB0_206

; __global__ void __launch_bounds__(NWAVES * 64, 2) mega(Args args) {
;     ...
;             for (int u = bx; u < DECB * 4; u += G) {
;                 const int b = u >> 2, hs = u & 3;
;                 __syncthreads();
;                 for (int j = wave; j < 12; j += NWAVES) {
;                     const int g = j >> 2, qi = j & 3;
;                     attn_tile<true>(Qb, Kb, Vb, args.in[2], args.in[3], args.in[4], l, otile + j * 128, lsel + g * 4 + qi, vl, b, g * 4 + hs, qi, 0, lane);
;                 }
;                 __syncthreads();
;                 if (tid < 96) {
;                     const int j = tid >> 3, seg = tid & 7, g = j >> 2, qi = j & 3;
.LBB0_1583:
	s_or_b64 exec, exec, s[6:7]
	v_readlane_b32 s0, v253, 31
	v_readlane_b32 s1, v253, 32
	v_readlane_b32 s24, v250, 4
	v_readlane_b32 s26, v253, 25
	s_mov_b64 vcc, 0
	v_ashrrev_i32_e32 v136, 4, v134
	v_ashrrev_i32_e32 v133, 3, v134
	v_lshlrev_b32_e32 v141, 3, v134
	v_lshlrev_b32_e32 v161, 4, v134
	v_and_b32_e32 v0, 7, v134
	s_movk_i32 s0, 0xa0
	v_readlane_b32 s25, v250, 5
	v_readlane_b32 s27, v253, 26
	v_and_b32_e32 v160, 15, v134
	v_bfe_u32 v145, v134, 2, 2
	v_cmp_gt_u32_e64 s[36:37], 16, v134
	v_lshlrev_b32_e32 v138, 3, v136
	v_and_b32_e32 v162, 24, v141
	v_and_b32_e32 v142, 0x70, v161
	v_mul_lo_u32 v163, v133, s0
	v_ashrrev_i32_e32 v135, 3, v132
	v_lshlrev_b32_e32 v164, 4, v0
	v_lshlrev_b32_e32 v140, 3, v0
	s_cbranch_vccnz .LBB0_1710
	v_readlane_b32 s0, v250, 39
	v_readlane_b32 s1, v250, 40
	s_lshl_b32 s2, s0, 5
	v_and_b32_e32 v144, 56, v141
	v_readlane_b32 s0, v252, 13
	v_lshlrev_b32_e32 v0, 1, v144
	v_mov_b32_e32 v1, v2
	v_readlane_b32 s1, v252, 14
	v_ashrrev_i32_e32 v139, 31, v138
	v_lshl_or_b32 v3, v136, 2, v145
	v_lshl_add_u64 v[146:147], s[0:1], 0, v[0:1]
	v_add_u32_e32 v0, 8, v133
	v_min_i32_e32 v143, 0x80, v0
	v_add_u32_e32 v0, 16, v133
	v_min_i32_e32 v165, 0x80, v0
	v_add_u32_e32 v0, 24, v133
	v_min_i32_e32 v166, 0x80, v0
	v_min_i32_e32 v0, 0x60, v133
	v_add_u32_e32 v167, 32, v0
	v_min_i32_e32 v0, 0x58, v133
	v_add_u32_e32 v180, 40, v0
	v_min_i32_e32 v0, 0x50, v133
	v_add_u32_e32 v181, 48, v0
	v_min_i32_e32 v0, 0x48, v133
	v_add_u32_e32 v182, 56, v0
	v_min_i32_e32 v0, 64, v133
	v_add_u32_e32 v183, 64, v0
	v_min_i32_e32 v0, 56, v133
	v_add_u32_e32 v184, 0x48, v0
	v_min_i32_e32 v0, 48, v133
	v_add_u32_e32 v185, 0x50, v0
	v_min_i32_e32 v0, 40, v133
	v_add_u32_e32 v186, 0x58, v0
	v_min_i32_e32 v0, 32, v133
	v_add_u32_e32 v187, 0x60, v0
	v_min_i32_e32 v0, 24, v133
	v_add_u32_e32 v188, 0x68, v0
	v_min_i32_e32 v0, 16, v133
	v_add_u32_e32 v189, 0x70, v0
	v_min_i32_e32 v0, 8, v133
	v_add_u32_e32 v190, 0x78, v0
	v_min_i32_e32 v0, 0, v133
	v_add_u32_e32 v191, 0x80, v0
	v_min_i32_e32 v0, -8, v133
	v_add_u32_e32 v192, 0x88, v0
	v_min_i32_e32 v0, -16, v133
	v_add_u32_e32 v193, 0x90, v0
	v_min_i32_e32 v0, 0xffffffe8, v133
	v_readlane_b32 s0, v252, 11
	v_add_u32_e32 v194, 0x98, v0
	v_lshlrev_b64 v[0:1], 1, v[138:139]
	v_readlane_b32 s1, v252, 12
	v_ashrrev_i32_e32 v5, 3, v132
	s_waitcnt lgkmcnt(0)
	v_and_b32_e32 v7, 3, v5
	v_lshl_add_u64 v[148:149], s[0:1], 0, v[0:1]
	s_movk_i32 s0, 0xa0
	v_mul_lo_u32 v3, v3, s0
	v_readlane_b32 s0, v253, 22
	v_ashrrev_i32_e32 v6, 5, v132
	v_lshl_add_u32 v5, v5, 7, 0
	v_add_u32_e32 v3, s0, v3
	v_add_u32_e32 v4, s0, v142
	s_movk_i32 s0, 0x60
	v_cmp_gt_i32_e64 s[44:45], s0, v132
	s_add_i32 s0, 0, 0x22000
	v_lshl_add_u32 v202, v7, 2, s0
	v_readlane_b32 s0, v254, 57
	v_min_i32_e32 v137, 0x80, v133
	v_or_b32_e32 v195, 16, v160
	v_or_b32_e32 v196, 32, v160
	v_or_b32_e32 v197, 48, v160
	v_or_b32_e32 v198, 64, v160
	v_or_b32_e32 v199, 0x50, v160
	v_or_b32_e32 v200, 0x60, v160
	v_or_b32_e32 v201, 0x70, v160
	v_cmp_lt_i32_e64 s[38:39], 0, v136
	v_cmp_gt_i32_e64 s[40:41], 0, v136
	v_cmp_eq_u32_e64 s[42:43], 0, v160
	v_cmp_gt_u32_e64 s[46:47], 32, v132
	v_cmp_eq_u32_e64 s[48:49], 1, v6
	v_or_b32_e32 v150, 0x4000, v7
	v_mov_b32_e32 v151, v2
	v_lshlrev_b32_e32 v203, 8, v6
	v_lshl_add_u64 v[152:153], s[88:89], 0, v[0:1]
	v_add_u32_e32 v204, s0, v138
	v_add_u32_e32 v205, v4, v163
	v_add_u32_e32 v206, v3, v162
	v_add_u32_e32 v207, v5, v164
	v_lshlrev_b32_e32 v154, 1, v140
	v_lshrrev_b32_e32 v0, 4, v132
	v_xor_b32_e32 v0, s91, v0
	v_and_b32_e32 v0, 1, v0
	v_cmp_eq_u32_e32 vcc, 0, v0
	s_and_b64 s[44:45], s[44:45], vcc
	s_lshr_b32 s8, s91, 1
	s_branch .LBB0_1586

; __global__ void __launch_bounds__(NWAVES * 64, 2) mega(Args args) {
;     ...
;             for (int u = bx; u < DECB * 4; u += G) {
;                 const int b = u >> 2, hs = u & 3;
;                 __syncthreads();
;                 for (int j = wave; j < 12; j += NWAVES) {
;                     const int g = j >> 2, qi = j & 3;
;                     attn_tile<true>(Qb, Kb, Vb, args.in[2], args.in[3], args.in[4], l, otile + j * 128, lsel + g * 4 + qi, vl, b, g * 4 + hs, qi, 0, lane);
;                 }
.LBB0_1586:
	s_and_b32 s9, s8, 3
	s_andn2_b64 vcc, exec, s[26:27]
	s_waitcnt vmcnt(0)
	s_barrier
	s_cbranch_vccnz .LBB0_1708
	s_lshr_b32 s0, s86, 1
	s_xor_b32 s0, s0, s91
	s_and_b32 s0, s0, 1
	s_cmp_lg_u32 s0, 0
	s_cbranch_scc1 .LBB0_1708
	v_and_b32_e32 v1, 64, v219
	v_xor_b32_e32 v0, 16, v219
	v_add_u32_e32 v1, 64, v1
	s_and_b32 s1, s8, -4
	v_cmp_lt_i32_e32 vcc, v0, v1
	s_ashr_i32 s0, s8, 2
	s_ashr_i32 s4, s1, 31
	v_cndmask_b32_e32 v0, v219, v0, vcc
	s_add_u32 s6, s1, 0x4000
	v_lshlrev_b32_e32 v155, 2, v0
	v_xor_b32_e32 v0, 32, v219
	s_addc_u32 s7, s4, 0
	s_add_i32 s52, s0, s2
	v_cmp_lt_i32_e32 vcc, v0, v1
	s_or_b32 s0, s6, s33
	s_mul_i32 s4, s7, 0x600
	v_cndmask_b32_e32 v0, v219, v0, vcc
	v_mad_u64_u32 v[156:157], s[0:1], s0, v231, v[152:153]
	s_ashr_i32 s53, s52, 31
	v_lshlrev_b32_e32 v208, 2, v0
	v_add_u32_e32 v157, s4, v157
	v_readlane_b32 s20, v254, 58
	v_mov_b32_e32 v209, v204
	s_mov_b32 s21, s86
	s_branch .LBB0_1589

; __global__ void __launch_bounds__(NWAVES * 64, 2) mega(Args args) {
;     ...
;             const int nsgu = G == 256 ? (bx < 128 ? 1 : 3) : (128 * 4 - bx + G - 1) / G;
;             for (int ui = 0; ui < nsgu; ++ui) {
;                 const int unit = G == 256 ? (bx < 128 ? bx : 128 + 3 * (bx - 128) + ui) : bx + ui * G;
.LBB0_1760:
	s_andn2_b64 vcc, exec, s[0:1]
	s_cbranch_vccnz .LBB0_1762
	v_readlane_b32 s0, v253, 34
	s_add_i32 s4, s0, s8
	v_readlane_b32 s0, v253, 31
	v_readlane_b32 s1, v253, 32
	s_and_b64 s[0:1], s[0:1], exec
	s_nop 0
